# in-proj epilogue: gate-column heads of PROJ (read three phases later) stored with nt; other heads default (on top of nt4)
# baseline (speedup 1.0000x reference)
; __device__ __forceinline__ unsigned cvt_pk_bf16(float lo, float hi) { unsigned r; asm volatile("v_cvt_pk_bf16_f32 %0, %1, %2" : "=v"(r) : "v"(lo), "v"(hi)); return r; }
;     __device__ __forceinline__ void operator()(const f32x4 (&acc)[2][2][4][2], const Unit& u, int wr, int wc, int fr, int fq) const {
;         const int row0 = u.pm * BM + wr * 64 + fr, col0 = wc * 32 + 8 * fq;
; #pragma unroll
;         for (int ai = 0; ai < 2; ++ai) {
;             f32x4 pa[4], pb[4];
; #pragma unroll
;             for (int m = 0; m < 4; ++m) { const f32x4* pp = (const f32x4*)(rowsq + (size_t)(row0 + ai * HALF + m * 16) * 32 + 8 * fq); pa[m] = pp[0]; pb[m] = pp[1]; }
; #pragma unroll
;             for (int m = 0; m < 4; ++m) { const int row = row0 + ai * HALF + m * 16; const f32x4 a = pa[m], b = pb[m];
;                 float sq = ((a[0] + a[1]) + (a[2] + a[3])) + ((b[0] + b[1]) + (b[2] + b[3])); sq += __shfl_xor(sq, 16); sq += __shfl_xor(sq, 32);
;                 const float rs = __builtin_amdgcn_rsqf(sq * inv_k + eps);
; #pragma unroll
;                 for (int bj = 0; bj < 2; ++bj) { const f32x4 v0 = acc[ai][bj][m][0] * rs, v1 = acc[ai][bj][m][1] * rs;
;                     u32x4 w; w.x = cvt_pk_bf16(v0[0], v0[1]); w.y = cvt_pk_bf16(v0[2], v0[3]); w.z = cvt_pk_bf16(v1[0], v1[1]); w.w = cvt_pk_bf16(v1[2], v1[3]);
;                     *(u32x4*)(O + ((size_t)(u.pn * 2 + bj) * Mrows + row) * HALF + col0) = w; } }
;             asm volatile("" ::: "memory"); }
.LBB0_217:
	v_cmp_lt_i32_e32 vcc, v224, v219
	v_lshl_add_u32 v168, s36, 8, v176
	v_ashrrev_i32_e32 v169, 31, v168
	v_cndmask_b32_e32 v114, v218, v224, vcc
	v_cmp_lt_i32_e32 vcc, v225, v219
	v_lshlrev_b32_e32 v180, 2, v114
	v_or_b32_e32 v174, 16, v168
	v_cndmask_b32_e32 v114, v218, v225, vcc
	v_lshlrev_b32_e32 v179, 2, v114
	v_lshlrev_b64 v[114:115], 7, v[168:169]
	v_lshl_add_u64 v[114:115], v[162:163], 0, v[114:115]
	global_load_dwordx4 v[182:185], v[114:115], off
	global_load_dwordx4 v[186:189], v[114:115], off offset:16
	v_ashrrev_i32_e32 v175, 31, v174
	v_lshlrev_b64 v[114:115], 7, v[174:175]
	v_lshl_add_u64 v[114:115], v[162:163], 0, v[114:115]
	global_load_dwordx4 v[146:149], v[114:115], off
	global_load_dwordx4 v[150:153], v[114:115], off offset:16
	v_or_b32_e32 v172, 32, v168
	v_ashrrev_i32_e32 v173, 31, v172
	v_lshlrev_b64 v[114:115], 7, v[172:173]
	v_lshl_add_u64 v[114:115], v[162:163], 0, v[114:115]
	global_load_dwordx4 v[134:137], v[114:115], off
	global_load_dwordx4 v[130:133], v[114:115], off offset:16
	v_or_b32_e32 v170, 48, v168
	v_ashrrev_i32_e32 v171, 31, v170
	v_lshlrev_b64 v[114:115], 7, v[170:171]
	v_lshl_add_u64 v[114:115], v[162:163], 0, v[114:115]
	global_load_dwordx4 v[118:121], v[114:115], off
	s_nop 0
	global_load_dwordx4 v[114:117], v[114:115], off offset:16
	s_sub_i32 s82, s14, 6
	s_cmp_lt_u32 s82, 4
	s_cselect_b32 s83, 1, 0
	s_sub_i32 s82, s14, 22
	s_cmp_lt_u32 s82, 4
	s_cselect_b32 s82, 1, 0
	s_or_b32 s82, s82, s83
	s_lshl_b32 s14, s14, 1
	s_cmp_eq_u32 s27, s85
	s_cselect_b64 s[80:81], 0, -1
	s_cbranch_scc0 .Ltail_c
	s_lshr_b32 s15, s49, 7
	s_add_i32 s14, s14, s15
.Ltail_c:
	s_ashr_i32 s15, s14, 31
	s_lshl_b64 s[34:35], s[14:15], 14
	s_or_b32 s14, s14, 1
	s_ashr_i32 s15, s14, 31
	s_lshl_b64 s[36:37], s[14:15], 14
	s_andn2_b64 vcc, exec, s[38:39]
	s_waitcnt vmcnt(0)
	v_mov_b32_e32 v190, v182
	v_mov_b32_e32 v191, v186
	v_mov_b32_e32 v186, v183
	v_pk_add_f32 v[182:183], v[190:191], v[186:187]
	v_mov_b32_e32 v186, v184
	v_mov_b32_e32 v187, v188
	v_mov_b32_e32 v188, v185
	v_pk_add_f32 v[184:185], v[186:187], v[188:189]
	s_nop 0
	v_pk_add_f32 v[182:183], v[182:183], v[184:185]
	s_nop 0
	v_add_f32_e32 v181, v182, v183
	v_mov_b32_e32 v182, v181
	s_nop 1
	v_permlane16_swap_b32_e32 v181, v182
	v_add_f32_e32 v181, v181, v182
	v_mov_b32_e32 v182, v181
	s_nop 1
	v_permlane32_swap_b32_e32 v181, v182
	v_add_f32_e32 v181, v181, v182
	v_fmamk_f32 v181, v181, 0x3a000000, v215
	v_rsq_f32_e32 v182, v181
	s_nop 0
	v_pk_mul_f32 v[142:143], v[142:143], v[182:183] op_sel_hi:[1,0]
	v_pk_mul_f32 v[184:185], v[140:141], v[182:183] op_sel_hi:[1,0]
	v_pk_mul_f32 v[140:141], v[138:139], v[182:183] op_sel_hi:[1,0]
	v_cvt_pk_bf16_f32 v138, v142, v143
	v_lshl_add_u64 v[142:143], s[34:35], 0, v[168:169]
	v_lshlrev_b64 v[142:143], 8, v[142:143]
	v_pk_mul_f32 v[144:145], v[144:145], v[182:183] op_sel_hi:[1,0]
	v_lshl_add_u64 v[142:143], v[160:161], 0, v[142:143]
	v_cvt_pk_bf16_f32 v139, v144, v145
	v_pk_mul_f32 v[126:127], v[126:127], v[182:183] op_sel_hi:[1,0]
	v_cvt_pk_bf16_f32 v140, v140, v141
	v_cvt_pk_bf16_f32 v141, v184, v185
	s_cmp_lg_u32 s82, 0
	s_cbranch_scc1 .Lgnt_0
	global_store_dwordx4 v[142:143], v[138:141], off
	s_branch .Lgd_0
.Lgnt_0:
	global_store_dwordx4 v[142:143], v[138:141], off nt
.Lgd_0:
	v_pk_mul_f32 v[128:129], v[128:129], v[182:183] op_sel_hi:[1,0]
	s_nop 0
	v_pk_mul_f32 v[138:139], v[124:125], v[182:183] op_sel_hi:[1,0]
	v_pk_mul_f32 v[124:125], v[122:123], v[182:183] op_sel_hi:[1,0]
	v_cvt_pk_bf16_f32 v122, v126, v127
	v_lshl_add_u64 v[126:127], s[36:37], 0, v[168:169]
	v_lshlrev_b64 v[126:127], 8, v[126:127]
	v_cvt_pk_bf16_f32 v123, v128, v129
	v_cvt_pk_bf16_f32 v124, v124, v125
	v_cvt_pk_bf16_f32 v125, v138, v139
	v_lshl_add_u64 v[126:127], v[160:161], 0, v[126:127]
	s_mov_b64 exec, s[80:81]
	s_cmp_lg_u32 s82, 0
	s_cbranch_scc1 .Lgnt_1
	global_store_dwordx4 v[126:127], v[122:125], off
	s_branch .Lgd_1
.Lgnt_1:
	global_store_dwordx4 v[126:127], v[122:125], off nt
.Lgd_1:
	s_mov_b64 exec, -1
	s_nop 1
	v_mov_b32_e32 v122, v146
	v_mov_b32_e32 v123, v150
	v_mov_b32_e32 v150, v147
	v_mov_b32_e32 v124, v148
	v_mov_b32_e32 v125, v152
	v_mov_b32_e32 v152, v149
	v_pk_add_f32 v[122:123], v[122:123], v[150:151]
	v_pk_add_f32 v[124:125], v[124:125], v[152:153]
	s_nop 0
	v_pk_add_f32 v[122:123], v[122:123], v[124:125]
	s_nop 0
	v_add_f32_e32 v122, v122, v123
	v_mov_b32_e32 v123, v122
	s_nop 1
	v_permlane16_swap_b32_e32 v122, v123
	v_add_f32_e32 v122, v122, v123
	v_mov_b32_e32 v123, v122
	s_nop 1
	v_permlane32_swap_b32_e32 v122, v123
	v_add_f32_e32 v122, v122, v123
	v_fmamk_f32 v122, v122, 0x3a000000, v215
	v_rsq_f32_e32 v122, v122
	s_nop 0
	v_pk_mul_f32 v[110:111], v[110:111], v[122:123] op_sel_hi:[1,0]
	v_pk_mul_f32 v[124:125], v[108:109], v[122:123] op_sel_hi:[1,0]
	v_pk_mul_f32 v[108:109], v[106:107], v[122:123] op_sel_hi:[1,0]
	v_cvt_pk_bf16_f32 v106, v110, v111
	v_lshl_add_u64 v[110:111], s[34:35], 0, v[174:175]
	v_lshlrev_b64 v[110:111], 8, v[110:111]
	v_pk_mul_f32 v[112:113], v[112:113], v[122:123] op_sel_hi:[1,0]
	v_lshl_add_u64 v[110:111], v[160:161], 0, v[110:111]
	v_cvt_pk_bf16_f32 v107, v112, v113
	v_pk_mul_f32 v[102:103], v[102:103], v[122:123] op_sel_hi:[1,0]
	v_cvt_pk_bf16_f32 v108, v108, v109
	v_cvt_pk_bf16_f32 v109, v124, v125
	s_cmp_lg_u32 s82, 0
	s_cbranch_scc1 .Lgnt_2
	global_store_dwordx4 v[110:111], v[106:109], off
	s_branch .Lgd_2
.Lgnt_2:
	global_store_dwordx4 v[110:111], v[106:109], off nt
; __device__ __forceinline__ unsigned cvt_pk_bf16(float lo, float hi) { unsigned r; asm volatile("v_cvt_pk_bf16_f32 %0, %1, %2" : "=v"(r) : "v"(lo), "v"(hi)); return r; }
;     __device__ __forceinline__ void operator()(const f32x4 (&acc)[2][2][4][2], const Unit& u, int wr, int wc, int fr, int fq) const {
;         const int row0 = u.pm * BM + wr * 64 + fr, col0 = wc * 32 + 8 * fq;
; #pragma unroll
;         for (int ai = 0; ai < 2; ++ai) {
;             f32x4 pa[4], pb[4];
; #pragma unroll
;             for (int m = 0; m < 4; ++m) { const f32x4* pp = (const f32x4*)(rowsq + (size_t)(row0 + ai * HALF + m * 16) * 32 + 8 * fq); pa[m] = pp[0]; pb[m] = pp[1]; }
; #pragma unroll
;             for (int m = 0; m < 4; ++m) { const int row = row0 + ai * HALF + m * 16; const f32x4 a = pa[m], b = pb[m];
;                 float sq = ((a[0] + a[1]) + (a[2] + a[3])) + ((b[0] + b[1]) + (b[2] + b[3])); sq += __shfl_xor(sq, 16); sq += __shfl_xor(sq, 32);
;                 const float rs = __builtin_amdgcn_rsqf(sq * inv_k + eps);
; #pragma unroll
;                 for (int bj = 0; bj < 2; ++bj) { const f32x4 v0 = acc[ai][bj][m][0] * rs, v1 = acc[ai][bj][m][1] * rs;
;                     u32x4 w; w.x = cvt_pk_bf16(v0[0], v0[1]); w.y = cvt_pk_bf16(v0[2], v0[3]); w.z = cvt_pk_bf16(v1[0], v1[1]); w.w = cvt_pk_bf16(v1[2], v1[3]);
;                     *(u32x4*)(O + ((size_t)(u.pn * 2 + bj) * Mrows + row) * HALF + col0) = w; } }
;             asm volatile("" ::: "memory"); }
.Lgd_2:
	v_pk_mul_f32 v[104:105], v[104:105], v[122:123] op_sel_hi:[1,0]
	s_nop 0
	v_pk_mul_f32 v[106:107], v[100:101], v[122:123] op_sel_hi:[1,0]
	v_pk_mul_f32 v[100:101], v[98:99], v[122:123] op_sel_hi:[1,0]
	v_cvt_pk_bf16_f32 v98, v102, v103
	v_lshl_add_u64 v[102:103], s[36:37], 0, v[174:175]
	v_lshlrev_b64 v[102:103], 8, v[102:103]
	v_cvt_pk_bf16_f32 v99, v104, v105
	v_cvt_pk_bf16_f32 v100, v100, v101
	v_cvt_pk_bf16_f32 v101, v106, v107
	v_lshl_add_u64 v[102:103], v[160:161], 0, v[102:103]
	s_mov_b64 exec, s[80:81]
	s_cmp_lg_u32 s82, 0
	s_cbranch_scc1 .Lgnt_3
	global_store_dwordx4 v[102:103], v[98:101], off
	s_branch .Lgd_3
.Lgnt_3:
	global_store_dwordx4 v[102:103], v[98:101], off nt
.Lgd_3:
	s_mov_b64 exec, -1
	v_add_u32_e32 v104, 0x80, v168
	v_ashrrev_i32_e32 v105, 31, v104
	v_mov_b32_e32 v98, v134
	v_mov_b32_e32 v99, v130
	v_mov_b32_e32 v130, v135
	v_mov_b32_e32 v100, v136
	v_mov_b32_e32 v101, v132
	v_mov_b32_e32 v132, v137
	v_pk_add_f32 v[98:99], v[98:99], v[130:131]
	v_pk_add_f32 v[100:101], v[100:101], v[132:133]
	s_nop 0
	v_pk_add_f32 v[98:99], v[98:99], v[100:101]
	s_nop 0
	v_add_f32_e32 v98, v98, v99
	v_mov_b32_e32 v99, v98
	s_nop 1
	v_permlane16_swap_b32_e32 v98, v99
	v_add_f32_e32 v98, v98, v99
	v_mov_b32_e32 v99, v98
	s_nop 1
	v_permlane32_swap_b32_e32 v98, v99
	v_add_f32_e32 v98, v98, v99
	v_fmamk_f32 v98, v98, 0x3a000000, v215
	v_rsq_f32_e32 v98, v98
	s_nop 0
	v_pk_mul_f32 v[94:95], v[94:95], v[98:99] op_sel_hi:[1,0]
	v_pk_mul_f32 v[100:101], v[92:93], v[98:99] op_sel_hi:[1,0]
	v_pk_mul_f32 v[92:93], v[90:91], v[98:99] op_sel_hi:[1,0]
	v_cvt_pk_bf16_f32 v90, v94, v95
	v_lshl_add_u64 v[94:95], s[34:35], 0, v[172:173]
	v_lshlrev_b64 v[94:95], 8, v[94:95]
	v_pk_mul_f32 v[96:97], v[96:97], v[98:99] op_sel_hi:[1,0]
	v_lshl_add_u64 v[94:95], v[160:161], 0, v[94:95]
	v_cvt_pk_bf16_f32 v91, v96, v97
	v_pk_mul_f32 v[86:87], v[86:87], v[98:99] op_sel_hi:[1,0]
	v_cvt_pk_bf16_f32 v92, v92, v93
	v_cvt_pk_bf16_f32 v93, v100, v101
	s_cmp_lg_u32 s82, 0
	s_cbranch_scc1 .Lgnt_4
	global_store_dwordx4 v[94:95], v[90:93], off
	s_branch .Lgd_4
.Lgnt_4:
	global_store_dwordx4 v[94:95], v[90:93], off nt
.Lgd_4:
	v_pk_mul_f32 v[88:89], v[88:89], v[98:99] op_sel_hi:[1,0]
	s_nop 0
	v_pk_mul_f32 v[90:91], v[84:85], v[98:99] op_sel_hi:[1,0]
	v_pk_mul_f32 v[84:85], v[82:83], v[98:99] op_sel_hi:[1,0]
	v_cvt_pk_bf16_f32 v82, v86, v87
	v_lshl_add_u64 v[86:87], s[36:37], 0, v[172:173]
	v_lshlrev_b64 v[86:87], 8, v[86:87]
	v_cvt_pk_bf16_f32 v83, v88, v89
	v_cvt_pk_bf16_f32 v84, v84, v85
	v_cvt_pk_bf16_f32 v85, v90, v91
	v_lshl_add_u64 v[86:87], v[160:161], 0, v[86:87]
	s_mov_b64 exec, s[80:81]
	s_cmp_lg_u32 s82, 0
	s_cbranch_scc1 .Lgnt_5
	global_store_dwordx4 v[86:87], v[82:85], off
	s_branch .Lgd_5
.Lgnt_5:
	global_store_dwordx4 v[86:87], v[82:85], off nt
.Lgd_5:
	s_mov_b64 exec, -1
	v_add_u32_e32 v86, 0x90, v168
	v_ashrrev_i32_e32 v87, 31, v86
	v_mov_b32_e32 v82, v118
	v_mov_b32_e32 v83, v114
	v_mov_b32_e32 v114, v119
	v_mov_b32_e32 v84, v120
	v_mov_b32_e32 v85, v116
	v_mov_b32_e32 v116, v121
	v_pk_add_f32 v[82:83], v[82:83], v[114:115]
	v_pk_add_f32 v[84:85], v[84:85], v[116:117]
	s_nop 0
	v_pk_add_f32 v[82:83], v[82:83], v[84:85]
	s_nop 0
	v_add_f32_e32 v82, v82, v83
	v_mov_b32_e32 v83, v82
	s_nop 1
	v_permlane16_swap_b32_e32 v82, v83
	v_add_f32_e32 v82, v82, v83
	v_mov_b32_e32 v83, v82
	s_nop 1
	v_permlane32_swap_b32_e32 v82, v83
	v_add_f32_e32 v82, v82, v83
	v_fmamk_f32 v82, v82, 0x3a000000, v215
	v_rsq_f32_e32 v82, v82
	s_nop 0
	v_pk_mul_f32 v[78:79], v[78:79], v[82:83] op_sel_hi:[1,0]
	v_pk_mul_f32 v[84:85], v[76:77], v[82:83] op_sel_hi:[1,0]
	v_pk_mul_f32 v[76:77], v[74:75], v[82:83] op_sel_hi:[1,0]
	v_cvt_pk_bf16_f32 v74, v78, v79
	v_lshl_add_u64 v[78:79], s[34:35], 0, v[170:171]
	v_lshlrev_b64 v[78:79], 8, v[78:79]
	v_pk_mul_f32 v[80:81], v[80:81], v[82:83] op_sel_hi:[1,0]
	v_lshl_add_u64 v[78:79], v[160:161], 0, v[78:79]
	v_cvt_pk_bf16_f32 v75, v80, v81
	v_pk_mul_f32 v[70:71], v[70:71], v[82:83] op_sel_hi:[1,0]
	v_cvt_pk_bf16_f32 v76, v76, v77
	v_cvt_pk_bf16_f32 v77, v84, v85
	s_cmp_lg_u32 s82, 0
	s_cbranch_scc1 .Lgnt_6
	global_store_dwordx4 v[78:79], v[74:77], off
	s_branch .Lgd_6
.Lgnt_6:
	global_store_dwordx4 v[78:79], v[74:77], off nt
.Lgd_6:
	v_pk_mul_f32 v[72:73], v[72:73], v[82:83] op_sel_hi:[1,0]
	v_add_u32_e32 v84, 0xa0, v168
	v_pk_mul_f32 v[74:75], v[68:69], v[82:83] op_sel_hi:[1,0]
	v_pk_mul_f32 v[68:69], v[66:67], v[82:83] op_sel_hi:[1,0]
	v_cvt_pk_bf16_f32 v66, v70, v71
	v_lshl_add_u64 v[70:71], s[36:37], 0, v[170:171]
	v_lshlrev_b64 v[70:71], 8, v[70:71]
	v_cvt_pk_bf16_f32 v67, v72, v73
	v_lshl_add_u64 v[70:71], v[160:161], 0, v[70:71]
	v_cvt_pk_bf16_f32 v68, v68, v69
	v_cvt_pk_bf16_f32 v69, v74, v75
	s_mov_b64 exec, s[80:81]
	s_cmp_lg_u32 s82, 0
	s_cbranch_scc1 .Lgnt_7
	global_store_dwordx4 v[70:71], v[66:69], off
	s_branch .Lgd_7
.Lgnt_7:
	global_store_dwordx4 v[70:71], v[66:69], off nt
; __device__ __forceinline__ unsigned cvt_pk_bf16(float lo, float hi) { unsigned r; asm volatile("v_cvt_pk_bf16_f32 %0, %1, %2" : "=v"(r) : "v"(lo), "v"(hi)); return r; }
;     __device__ __forceinline__ void operator()(const f32x4 (&acc)[2][2][4][2], const Unit& u, int wr, int wc, int fr, int fq) const {
;         const int row0 = u.pm * BM + wr * 64 + fr, col0 = wc * 32 + 8 * fq;
; #pragma unroll
;         for (int ai = 0; ai < 2; ++ai) {
;             f32x4 pa[4], pb[4];
; #pragma unroll
;             for (int m = 0; m < 4; ++m) { const f32x4* pp = (const f32x4*)(rowsq + (size_t)(row0 + ai * HALF + m * 16) * 32 + 8 * fq); pa[m] = pp[0]; pb[m] = pp[1]; }
; #pragma unroll
;             for (int m = 0; m < 4; ++m) { const int row = row0 + ai * HALF + m * 16; const f32x4 a = pa[m], b = pb[m];
;                 float sq = ((a[0] + a[1]) + (a[2] + a[3])) + ((b[0] + b[1]) + (b[2] + b[3])); sq += __shfl_xor(sq, 16); sq += __shfl_xor(sq, 32);
;                 const float rs = __builtin_amdgcn_rsqf(sq * inv_k + eps);
; #pragma unroll
;                 for (int bj = 0; bj < 2; ++bj) { const f32x4 v0 = acc[ai][bj][m][0] * rs, v1 = acc[ai][bj][m][1] * rs;
;                     u32x4 w; w.x = cvt_pk_bf16(v0[0], v0[1]); w.y = cvt_pk_bf16(v0[2], v0[3]); w.z = cvt_pk_bf16(v1[0], v1[1]); w.w = cvt_pk_bf16(v1[2], v1[3]);
;                     *(u32x4*)(O + ((size_t)(u.pn * 2 + bj) * Mrows + row) * HALF + col0) = w; } }
;             asm volatile("" ::: "memory"); }
.Lgd_7:
	s_mov_b64 exec, -1
	v_ashrrev_i32_e32 v85, 31, v84
	v_add_u32_e32 v82, 0xb0, v168
	v_lshlrev_b64 v[66:67], 7, v[104:105]
	v_lshl_add_u64 v[66:67], v[162:163], 0, v[66:67]
	global_load_dwordx4 v[88:91], v[66:67], off
	global_load_dwordx4 v[92:95], v[66:67], off offset:16
	v_lshlrev_b64 v[66:67], 7, v[86:87]
	v_lshl_add_u64 v[66:67], v[162:163], 0, v[66:67]
	global_load_dwordx4 v[96:99], v[66:67], off
	global_load_dwordx4 v[100:103], v[66:67], off offset:16
	v_lshlrev_b64 v[66:67], 7, v[84:85]
	v_lshl_add_u64 v[66:67], v[162:163], 0, v[66:67]
	global_load_dwordx4 v[78:81], v[66:67], off
	global_load_dwordx4 v[74:77], v[66:67], off offset:16
	v_ashrrev_i32_e32 v83, 31, v82
	v_lshlrev_b64 v[66:67], 7, v[82:83]
	v_lshl_add_u64 v[66:67], v[162:163], 0, v[66:67]
	global_load_dwordx4 v[70:73], v[66:67], off
	s_nop 0
	global_load_dwordx4 v[66:69], v[66:67], off offset:16
	s_waitcnt vmcnt(7)
	v_mov_b32_e32 v106, v88
	s_waitcnt vmcnt(6)
	v_mov_b32_e32 v107, v92
	v_mov_b32_e32 v92, v89
	v_pk_add_f32 v[88:89], v[106:107], v[92:93]
	v_mov_b32_e32 v92, v90
	v_mov_b32_e32 v93, v94
	v_mov_b32_e32 v94, v91
	v_pk_add_f32 v[90:91], v[92:93], v[94:95]
	s_nop 0
	v_pk_add_f32 v[88:89], v[88:89], v[90:91]
	s_nop 0
	v_add_f32_e32 v88, v88, v89
	v_mov_b32_e32 v89, v88
	s_nop 1
	v_permlane16_swap_b32_e32 v88, v89
	v_add_f32_e32 v88, v88, v89
	v_mov_b32_e32 v89, v88
	s_nop 1
	v_permlane32_swap_b32_e32 v88, v89
	v_add_f32_e32 v88, v88, v89
	v_fmamk_f32 v88, v88, 0x3a000000, v215
	v_rsq_f32_e32 v88, v88
	s_nop 0
	v_pk_mul_f32 v[62:63], v[62:63], v[88:89] op_sel_hi:[1,0]
	v_pk_mul_f32 v[90:91], v[60:61], v[88:89] op_sel_hi:[1,0]
	v_pk_mul_f32 v[60:61], v[58:59], v[88:89] op_sel_hi:[1,0]
	v_cvt_pk_bf16_f32 v58, v62, v63
	v_lshl_add_u64 v[62:63], s[34:35], 0, v[104:105]
	v_lshlrev_b64 v[62:63], 8, v[62:63]
	v_pk_mul_f32 v[64:65], v[64:65], v[88:89] op_sel_hi:[1,0]
	v_lshl_add_u64 v[62:63], v[160:161], 0, v[62:63]
	v_cvt_pk_bf16_f32 v59, v64, v65
	v_pk_mul_f32 v[54:55], v[54:55], v[88:89] op_sel_hi:[1,0]
	v_cvt_pk_bf16_f32 v60, v60, v61
	v_cvt_pk_bf16_f32 v61, v90, v91
	s_cmp_lg_u32 s82, 0
	s_cbranch_scc1 .Lgnt_8
	global_store_dwordx4 v[62:63], v[58:61], off
	s_branch .Lgd_8
.Lgnt_8:
	global_store_dwordx4 v[62:63], v[58:61], off nt
.Lgd_8:
	v_pk_mul_f32 v[56:57], v[56:57], v[88:89] op_sel_hi:[1,0]
	s_nop 0
	v_pk_mul_f32 v[58:59], v[52:53], v[88:89] op_sel_hi:[1,0]
	v_pk_mul_f32 v[52:53], v[50:51], v[88:89] op_sel_hi:[1,0]
	v_cvt_pk_bf16_f32 v50, v54, v55
	v_lshl_add_u64 v[54:55], s[36:37], 0, v[104:105]
	v_lshlrev_b64 v[54:55], 8, v[54:55]
	v_cvt_pk_bf16_f32 v51, v56, v57
	v_cvt_pk_bf16_f32 v52, v52, v53
	v_cvt_pk_bf16_f32 v53, v58, v59
	v_lshl_add_u64 v[54:55], v[160:161], 0, v[54:55]
	s_mov_b64 exec, s[80:81]
	s_cmp_lg_u32 s82, 0
	s_cbranch_scc1 .Lgnt_9
	global_store_dwordx4 v[54:55], v[50:53], off
	s_branch .Lgd_9
.Lgnt_9:
	global_store_dwordx4 v[54:55], v[50:53], off nt
.Lgd_9:
	s_mov_b64 exec, -1
	s_waitcnt vmcnt(7)
	s_nop 0
	v_mov_b32_e32 v50, v96
	s_waitcnt vmcnt(6)
	v_mov_b32_e32 v51, v100
	v_mov_b32_e32 v100, v97
	v_mov_b32_e32 v52, v98
	v_mov_b32_e32 v53, v102
	v_mov_b32_e32 v102, v99
	v_pk_add_f32 v[50:51], v[50:51], v[100:101]
	v_pk_add_f32 v[52:53], v[52:53], v[102:103]
	s_nop 0
	v_pk_add_f32 v[50:51], v[50:51], v[52:53]
	s_nop 0
	v_add_f32_e32 v50, v50, v51
	v_mov_b32_e32 v51, v50
	s_nop 1
	v_permlane16_swap_b32_e32 v50, v51
	v_add_f32_e32 v50, v50, v51
	v_mov_b32_e32 v51, v50
	s_nop 1
	v_permlane32_swap_b32_e32 v50, v51
	v_add_f32_e32 v50, v50, v51
	v_fmamk_f32 v50, v50, 0x3a000000, v215
	v_rsq_f32_e32 v50, v50
	s_nop 0
	v_pk_mul_f32 v[46:47], v[46:47], v[50:51] op_sel_hi:[1,0]
	v_pk_mul_f32 v[52:53], v[44:45], v[50:51] op_sel_hi:[1,0]
	v_pk_mul_f32 v[44:45], v[42:43], v[50:51] op_sel_hi:[1,0]
	v_cvt_pk_bf16_f32 v42, v46, v47
	v_lshl_add_u64 v[46:47], s[34:35], 0, v[86:87]
	v_lshlrev_b64 v[46:47], 8, v[46:47]
	v_pk_mul_f32 v[48:49], v[48:49], v[50:51] op_sel_hi:[1,0]
	v_lshl_add_u64 v[46:47], v[160:161], 0, v[46:47]
	v_cvt_pk_bf16_f32 v43, v48, v49
	v_pk_mul_f32 v[38:39], v[38:39], v[50:51] op_sel_hi:[1,0]
	v_cvt_pk_bf16_f32 v44, v44, v45
	v_cvt_pk_bf16_f32 v45, v52, v53
	s_cmp_lg_u32 s82, 0
	s_cbranch_scc1 .Lgnt_10
	global_store_dwordx4 v[46:47], v[42:45], off
	s_branch .Lgd_10
.Lgnt_10:
	global_store_dwordx4 v[46:47], v[42:45], off nt
; __device__ __forceinline__ unsigned cvt_pk_bf16(float lo, float hi) { unsigned r; asm volatile("v_cvt_pk_bf16_f32 %0, %1, %2" : "=v"(r) : "v"(lo), "v"(hi)); return r; }
; #define PG8_BAR __builtin_amdgcn_s_barrier()
;     __device__ __forceinline__ void operator()(const f32x4 (&acc)[2][2][4][2], const Unit& u, int wr, int wc, int fr, int fq) const {
;         const int row0 = u.pm * BM + wr * 64 + fr, col0 = wc * 32 + 8 * fq;
; #pragma unroll
;         for (int ai = 0; ai < 2; ++ai) {
;             f32x4 pa[4], pb[4];
; #pragma unroll
;             for (int m = 0; m < 4; ++m) { const f32x4* pp = (const f32x4*)(rowsq + (size_t)(row0 + ai * HALF + m * 16) * 32 + 8 * fq); pa[m] = pp[0]; pb[m] = pp[1]; }
; #pragma unroll
;             for (int m = 0; m < 4; ++m) { const int row = row0 + ai * HALF + m * 16; const f32x4 a = pa[m], b = pb[m];
;                 float sq = ((a[0] + a[1]) + (a[2] + a[3])) + ((b[0] + b[1]) + (b[2] + b[3])); sq += __shfl_xor(sq, 16); sq += __shfl_xor(sq, 32);
;                 const float rs = __builtin_amdgcn_rsqf(sq * inv_k + eps);
; #pragma unroll
;                 for (int bj = 0; bj < 2; ++bj) { const f32x4 v0 = acc[ai][bj][m][0] * rs, v1 = acc[ai][bj][m][1] * rs;
;                     u32x4 w; w.x = cvt_pk_bf16(v0[0], v0[1]); w.y = cvt_pk_bf16(v0[2], v0[3]); w.z = cvt_pk_bf16(v1[0], v1[1]); w.w = cvt_pk_bf16(v1[2], v1[3]);
;                     *(u32x4*)(O + ((size_t)(u.pn * 2 + bj) * Mrows + row) * HALF + col0) = w; } }
;             asm volatile("" ::: "memory"); }
; template <class Epi, class Sched, bool ALIGN_EPI = false, bool SP2 = false>
; __device__ __forceinline__ void gemm_phase(PG8_LAS unsigned char* lds, const Gemm g, const Sched& S, const Epi& E) {
;     ...
;         if constexpr (ALIGN_EPI) { if (wr == 0) PG8_BAR; }
;         if constexpr (!Epi::AFTER_DRAIN) { E(acc, cur, wr, wc, fr, fq); S.done(cur); }
;         if (!has_next) break;
.Lgd_10:
	v_pk_mul_f32 v[40:41], v[40:41], v[50:51] op_sel_hi:[1,0]
	s_nop 0
	v_pk_mul_f32 v[42:43], v[36:37], v[50:51] op_sel_hi:[1,0]
	v_pk_mul_f32 v[36:37], v[34:35], v[50:51] op_sel_hi:[1,0]
	v_cvt_pk_bf16_f32 v34, v38, v39
	v_lshl_add_u64 v[38:39], s[36:37], 0, v[86:87]
	v_lshlrev_b64 v[38:39], 8, v[38:39]
	v_cvt_pk_bf16_f32 v35, v40, v41
	v_cvt_pk_bf16_f32 v36, v36, v37
	v_cvt_pk_bf16_f32 v37, v42, v43
	v_lshl_add_u64 v[38:39], v[160:161], 0, v[38:39]
	s_mov_b64 exec, s[80:81]
	s_cmp_lg_u32 s82, 0
	s_cbranch_scc1 .Lgnt_11
	global_store_dwordx4 v[38:39], v[34:37], off
	s_branch .Lgd_11
.Lgnt_11:
	global_store_dwordx4 v[38:39], v[34:37], off nt
.Lgd_11:
	s_mov_b64 exec, -1
	s_waitcnt vmcnt(7)
	s_nop 0
	v_mov_b32_e32 v34, v78
	s_waitcnt vmcnt(6)
	v_mov_b32_e32 v35, v74
	v_mov_b32_e32 v74, v79
	v_mov_b32_e32 v36, v80
	v_mov_b32_e32 v37, v76
	v_mov_b32_e32 v76, v81
	v_pk_add_f32 v[34:35], v[34:35], v[74:75]
	v_pk_add_f32 v[36:37], v[36:37], v[76:77]
	s_nop 0
	v_pk_add_f32 v[34:35], v[34:35], v[36:37]
	s_nop 0
	v_add_f32_e32 v34, v34, v35
	v_mov_b32_e32 v35, v34
	s_nop 1
	v_permlane16_swap_b32_e32 v34, v35
	v_add_f32_e32 v34, v34, v35
	v_mov_b32_e32 v35, v34
	s_nop 1
	v_permlane32_swap_b32_e32 v34, v35
	v_add_f32_e32 v34, v34, v35
	v_fmamk_f32 v34, v34, 0x3a000000, v215
	v_rsq_f32_e32 v34, v34
	s_nop 0
	v_pk_mul_f32 v[30:31], v[30:31], v[34:35] op_sel_hi:[1,0]
	v_pk_mul_f32 v[36:37], v[28:29], v[34:35] op_sel_hi:[1,0]
	v_pk_mul_f32 v[28:29], v[26:27], v[34:35] op_sel_hi:[1,0]
	v_cvt_pk_bf16_f32 v26, v30, v31
	v_lshl_add_u64 v[30:31], s[34:35], 0, v[84:85]
	v_lshlrev_b64 v[30:31], 8, v[30:31]
	v_pk_mul_f32 v[32:33], v[32:33], v[34:35] op_sel_hi:[1,0]
	v_lshl_add_u64 v[30:31], v[160:161], 0, v[30:31]
	v_cvt_pk_bf16_f32 v27, v32, v33
	v_pk_mul_f32 v[22:23], v[22:23], v[34:35] op_sel_hi:[1,0]
	v_cvt_pk_bf16_f32 v28, v28, v29
	v_cvt_pk_bf16_f32 v29, v36, v37
	s_cmp_lg_u32 s82, 0
	s_cbranch_scc1 .Lgnt_12
	global_store_dwordx4 v[30:31], v[26:29], off
	s_branch .Lgd_12
.Lgnt_12:
	global_store_dwordx4 v[30:31], v[26:29], off nt
.Lgd_12:
	v_pk_mul_f32 v[24:25], v[24:25], v[34:35] op_sel_hi:[1,0]
	s_nop 0
	v_pk_mul_f32 v[26:27], v[20:21], v[34:35] op_sel_hi:[1,0]
	v_pk_mul_f32 v[20:21], v[18:19], v[34:35] op_sel_hi:[1,0]
	v_cvt_pk_bf16_f32 v18, v22, v23
	v_lshl_add_u64 v[22:23], s[36:37], 0, v[84:85]
	v_lshlrev_b64 v[22:23], 8, v[22:23]
	v_cvt_pk_bf16_f32 v19, v24, v25
	v_cvt_pk_bf16_f32 v20, v20, v21
	v_cvt_pk_bf16_f32 v21, v26, v27
	v_lshl_add_u64 v[22:23], v[160:161], 0, v[22:23]
	s_mov_b64 exec, s[80:81]
	s_cmp_lg_u32 s82, 0
	s_cbranch_scc1 .Lgnt_13
	global_store_dwordx4 v[22:23], v[18:21], off
	s_branch .Lgd_13
.Lgnt_13:
	global_store_dwordx4 v[22:23], v[18:21], off nt
.Lgd_13:
	s_mov_b64 exec, -1
	s_waitcnt vmcnt(7)
	s_nop 0
	v_mov_b32_e32 v18, v70
	s_waitcnt vmcnt(6)
	v_mov_b32_e32 v19, v66
	v_mov_b32_e32 v66, v71
	v_mov_b32_e32 v20, v72
	v_mov_b32_e32 v21, v68
	v_mov_b32_e32 v68, v73
	v_pk_add_f32 v[18:19], v[18:19], v[66:67]
	v_pk_add_f32 v[20:21], v[20:21], v[68:69]
	s_nop 0
	v_pk_add_f32 v[18:19], v[18:19], v[20:21]
	s_nop 0
	v_add_f32_e32 v18, v18, v19
	v_mov_b32_e32 v19, v18
	s_nop 1
	v_permlane16_swap_b32_e32 v18, v19
	v_add_f32_e32 v18, v18, v19
	v_mov_b32_e32 v19, v18
	s_nop 1
	v_permlane32_swap_b32_e32 v18, v19
	v_add_f32_e32 v18, v18, v19
	v_fmamk_f32 v18, v18, 0x3a000000, v215
	v_rsq_f32_e32 v18, v18
	s_nop 0
	v_pk_mul_f32 v[14:15], v[14:15], v[18:19] op_sel_hi:[1,0]
	v_pk_mul_f32 v[20:21], v[12:13], v[18:19] op_sel_hi:[1,0]
	v_pk_mul_f32 v[12:13], v[10:11], v[18:19] op_sel_hi:[1,0]
	v_cvt_pk_bf16_f32 v10, v14, v15
	v_lshl_add_u64 v[14:15], s[34:35], 0, v[82:83]
	v_lshlrev_b64 v[14:15], 8, v[14:15]
	v_pk_mul_f32 v[16:17], v[16:17], v[18:19] op_sel_hi:[1,0]
	v_lshl_add_u64 v[14:15], v[160:161], 0, v[14:15]
	v_cvt_pk_bf16_f32 v11, v16, v17
	v_pk_mul_f32 v[6:7], v[6:7], v[18:19] op_sel_hi:[1,0]
	v_cvt_pk_bf16_f32 v12, v12, v13
	v_cvt_pk_bf16_f32 v13, v20, v21
	s_cmp_lg_u32 s82, 0
	s_cbranch_scc1 .Lgnt_14
	global_store_dwordx4 v[14:15], v[10:13], off
	s_branch .Lgd_14
.Lgnt_14:
	global_store_dwordx4 v[14:15], v[10:13], off nt
.Lgd_14:
	v_pk_mul_f32 v[8:9], v[8:9], v[18:19] op_sel_hi:[1,0]
	s_mov_b64 s[34:35], -1
	v_pk_mul_f32 v[10:11], v[4:5], v[18:19] op_sel_hi:[1,0]
	v_pk_mul_f32 v[4:5], v[2:3], v[18:19] op_sel_hi:[1,0]
	v_cvt_pk_bf16_f32 v2, v6, v7
	v_lshl_add_u64 v[6:7], s[36:37], 0, v[82:83]
	v_lshlrev_b64 v[6:7], 8, v[6:7]
	v_lshl_add_u64 v[6:7], v[160:161], 0, v[6:7]
	v_cvt_pk_bf16_f32 v3, v8, v9
	v_cvt_pk_bf16_f32 v4, v4, v5
	v_cvt_pk_bf16_f32 v5, v10, v11
	s_mov_b64 exec, s[80:81]
	s_cmp_lg_u32 s82, 0
	s_cbranch_scc1 .Lgnt_15
	global_store_dwordx4 v[6:7], v[2:5], off
	s_branch .Lgd_15
.Lgnt_15:
	global_store_dwordx4 v[6:7], v[2:5], off nt
.Lgd_15:
	s_mov_b64 exec, -1
	s_cbranch_vccnz .LBB0_210
	s_andn2_b64 vcc, exec, s[0:1]
	s_cbranch_vccnz .LBB0_209
	s_barrier
	s_branch .LBB0_209
